# attention: static priority 1 for the younger half (waves 4-7, second softmax map) in its tile loop, reset at the unit epilogue
# baseline (speedup 1.0000x reference)
.LBB0_167:
	s_and_b32 s22, s8, 3
	s_lshl_b32 s8, s22, 5
	s_lshl_b32 s14, s3, 7
	v_and_b32_e32 v170, 31, v0
	s_or_b32 s36, s8, s14
	v_or_b32_e32 v128, s36, v170
	v_lshl_add_u64 v[2:3], s[74:75], 0, v[128:129]
	s_ashr_i32 s23, s9, 8
	v_lshlrev_b64 v[2:3], 12, v[2:3]
	v_lshl_add_u64 v[2:3], s[12:13], 0, v[2:3]
	s_lshl_b32 s14, s23, 6
	v_lshrrev_b32_e32 v169, 5, v166
	v_lshl_add_u64 v[2:3], v[2:3], 0, s[82:83]
	s_ashr_i32 s15, s14, 31
	v_lshl_add_u64 v[2:3], s[14:15], 1, v[2:3]
	v_lshlrev_b32_e32 v162, 4, v169
	v_mov_b32_e32 v163, v129
	v_lshl_add_u64 v[2:3], v[2:3], 0, v[162:163]
	global_load_dwordx4 v[130:133], v[2:3], off offset:96
	global_load_dwordx4 v[134:137], v[2:3], off offset:64
	global_load_dwordx4 v[138:141], v[2:3], off offset:32
	global_load_dwordx4 v[142:145], v[2:3], off
	s_lshl_b32 s67, s3, 1
	s_and_b32 s3, s9, 0x3fffffc0
	s_lshl_b32 s3, s3, 2
	s_lshl_b32 s8, s23, 13
	s_add_i32 s53, s3, 0
	s_add_i32 s20, s67, 2
	s_add_i32 s3, s8, 0
	s_lshr_b32 s14, s36, 6
	s_add_i32 s53, s53, 0x20400
	v_lshlrev_b32_e32 v2, 4, v0
	s_cmpk_lt_u32 s9, 0x100
	v_lshlrev_b32_e32 v0, 1, v0
	v_lshlrev_b32_e32 v3, 8, v169
	v_and_b32_e32 v2, 0xc0, v2
	s_cselect_b64 s[80:81], -1, 0
	s_cmp_gt_u32 s36, 63
	v_lshlrev_b32_e32 v1, 3, v1
	v_and_b32_e32 v0, 32, v0
	v_add3_u32 v2, 0, v3, v2
	s_cselect_b64 s[16:17], -1, 0
	s_waitcnt vmcnt(0)
	v_lshlrev_b32_e32 v4, 10, v169
	v_lshlrev_b32_e32 v5, 4, v170
	v_add3_u32 v163, v2, v0, v1
	v_cndmask_b32_e64 v0, 0, 1, s[16:17]
	s_mov_b64 s[40:41], -1
	v_add3_u32 v171, s3, v4, v5
	s_cmpk_gt_u32 s9, 0xff
	v_cmp_ne_u32_e64 s[38:39], 1, v0
	s_waitcnt vmcnt(0)
	s_barrier
	s_cbranch_scc0 .LBB0_225
	ds_read_b128 v[58:61], v171
	ds_read_b128 v[62:65], v171 offset:512
	ds_read_b128 v[54:57], v171 offset:2048
	ds_read_b128 v[50:53], v171 offset:2560
	ds_read_b128 v[46:49], v171 offset:4096
	ds_read_b128 v[42:45], v171 offset:4608
	ds_read_b128 v[38:41], v171 offset:6144
	ds_read_b128 v[34:37], v171 offset:6656
	s_and_b64 vcc, exec, s[38:39]
	s_cbranch_vccnz .LBB0_172
	s_setprio 1
	s_waitcnt lgkmcnt(7)
	v_mfma_f32_32x32x16_bf16 v[18:33], v[58:61], v[142:145], 0
	s_waitcnt lgkmcnt(6)
	v_mfma_f32_32x32x16_bf16 v[2:17], v[62:65], v[142:145], 0
	s_waitcnt lgkmcnt(5)
	v_mfma_f32_32x32x16_bf16 v[18:33], v[54:57], v[138:141], v[18:33]
	s_waitcnt lgkmcnt(4)
	v_mfma_f32_32x32x16_bf16 v[2:17], v[50:53], v[138:141], v[2:17]
	s_waitcnt lgkmcnt(3)
	v_mfma_f32_32x32x16_bf16 v[18:33], v[46:49], v[134:137], v[18:33]
	s_waitcnt lgkmcnt(2)
	v_mfma_f32_32x32x16_bf16 v[2:17], v[42:45], v[134:137], v[2:17]
	s_waitcnt lgkmcnt(1)
	v_mfma_f32_32x32x16_bf16 v[18:33], v[38:41], v[130:133], v[18:33]
	s_waitcnt lgkmcnt(0)
	v_mfma_f32_32x32x16_bf16 v[2:17], v[34:37], v[130:133], v[2:17]
	s_setprio 1
	s_nop 15
	s_nop 7
	v_cmp_gt_u32_e32 vcc, 32, v166
	v_max3_f32 v0, v18, v19, v2
	v_max3_f32 v1, v20, v21, v3
	s_nop 0
	v_max3_f32 v0, v0, v4, v5
	v_max3_f32 v1, v1, v24, v25
	s_nop 0
	v_max3_f32 v0, v0, v22, v23
	v_max3_f32 v1, v1, v8, v9
	s_nop 0
	v_max3_f32 v0, v0, v6, v7
	v_max3_f32 v1, v1, v28, v29
	s_nop 0
	v_max3_f32 v0, v0, v26, v27
	v_max3_f32 v1, v1, v12, v13
	s_nop 0
	v_max3_f32 v0, v0, v10, v11
	v_max3_f32 v1, v1, v32, v33
	s_nop 0
	v_max3_f32 v0, v0, v30, v31
	v_max3_f32 v1, v1, v16, v17
	s_nop 0
	v_max3_f32 v0, v0, v14, v15
	s_nop 0
	v_max_f32_e32 v0, v0, v1
	s_nop 0
	v_mov_b32_e32 v1, v0
	s_nop 1
	v_permlane32_swap_b32_e32 v0, v1
	v_max_f32_e32 v96, v0, v1
	s_nop 0
	v_exp_f32_e64 v97, -v96
	s_and_saveexec_b64 s[40:41], vcc
	v_lshl_add_u32 v0, v170, 2, s53
	ds_write_b32 v0, v97
	s_or_b64 exec, exec, s[40:41]
	v_mov_b32_e32 v1, v2
	v_mov_b32_e32 v2, v19
	v_pk_add_f32 v[68:69], v[2:3], v[96:97] op_sel_hi:[1,0] neg_lo:[0,1] neg_hi:[0,1]
	v_mov_b32_e32 v2, v20
	v_mov_b32_e32 v3, v4
	v_pk_add_f32 v[72:73], v[2:3], v[96:97] op_sel_hi:[1,0] neg_lo:[0,1] neg_hi:[0,1]
	v_mov_b32_e32 v2, v22
	v_mov_b32_e32 v3, v6
	v_pk_add_f32 v[70:71], v[2:3], v[96:97] op_sel_hi:[1,0] neg_lo:[0,1] neg_hi:[0,1]
	v_mov_b32_e32 v2, v24
	v_mov_b32_e32 v3, v8
	v_pk_add_f32 v[78:79], v[2:3], v[96:97] op_sel_hi:[1,0] neg_lo:[0,1] neg_hi:[0,1]
	v_mov_b32_e32 v2, v26
	v_mov_b32_e32 v3, v10
	v_pk_add_f32 v[82:83], v[2:3], v[96:97] op_sel_hi:[1,0] neg_lo:[0,1] neg_hi:[0,1]
	v_mov_b32_e32 v2, v28
	v_mov_b32_e32 v3, v12
	v_add_f32_e32 v173, 0, v96
	v_mov_b32_e32 v0, v18
	v_pk_add_f32 v[86:87], v[2:3], v[96:97] op_sel_hi:[1,0] neg_lo:[0,1] neg_hi:[0,1]
	v_mov_b32_e32 v2, v30
	v_mov_b32_e32 v3, v14
	s_waitcnt lgkmcnt(0)
	v_pk_add_f32 v[66:67], v[0:1], v[96:97] op_sel_hi:[1,0] neg_lo:[0,1] neg_hi:[0,1]
	v_xor_b32_e32 v0, 0x80000000, v173
	v_mov_b32_e32 v4, v21
	v_mov_b32_e32 v6, v23
	v_mov_b32_e32 v8, v25
	v_mov_b32_e32 v10, v27
	v_mov_b32_e32 v12, v29
	v_pk_add_f32 v[90:91], v[2:3], v[96:97] op_sel_hi:[1,0] neg_lo:[0,1] neg_hi:[0,1]
	v_mov_b32_e32 v14, v31
	v_mov_b32_e32 v2, v32
	v_mov_b32_e32 v3, v16
	v_mov_b32_e32 v16, v33
	v_pk_add_f32 v[76:77], v[4:5], v[96:97] op_sel_hi:[1,0] neg_lo:[0,1] neg_hi:[0,1]
	v_pk_add_f32 v[74:75], v[6:7], v[96:97] op_sel_hi:[1,0] neg_lo:[0,1] neg_hi:[0,1]
	v_pk_add_f32 v[80:81], v[8:9], v[96:97] op_sel_hi:[1,0] neg_lo:[0,1] neg_hi:[0,1]
	v_pk_add_f32 v[84:85], v[10:11], v[96:97] op_sel_hi:[1,0] neg_lo:[0,1] neg_hi:[0,1]
	v_pk_add_f32 v[88:89], v[12:13], v[96:97] op_sel_hi:[1,0] neg_lo:[0,1] neg_hi:[0,1]
	v_pk_add_f32 v[92:93], v[14:15], v[96:97] op_sel_hi:[1,0] neg_lo:[0,1] neg_hi:[0,1]
	v_pk_add_f32 v[94:95], v[2:3], v[96:97] op_sel_hi:[1,0] neg_lo:[0,1] neg_hi:[0,1]
	v_pk_add_f32 v[32:33], v[16:17], v[96:97] op_sel_hi:[1,0] neg_lo:[0,1] neg_hi:[0,1]
	v_mov_b32_e32 v1, v0
	v_mov_b32_e32 v2, v0
	v_mov_b32_e32 v3, v0
	v_mov_b32_e32 v4, v0
	v_mov_b32_e32 v5, v0
	v_mov_b32_e32 v6, v0
	v_mov_b32_e32 v7, v0
	v_mov_b32_e32 v8, v0
	v_mov_b32_e32 v9, v0
	v_mov_b32_e32 v10, v0
	v_mov_b32_e32 v11, v0
	v_mov_b32_e32 v12, v0
	v_mov_b32_e32 v13, v0
	v_mov_b32_e32 v14, v0
	v_mov_b32_e32 v15, v0
	s_mov_b64 s[40:41], 0
.LBB0_172:
	s_and_b64 vcc, exec, s[40:41]
	s_cbranch_vccz .LBB0_176
	s_setprio 1
	s_waitcnt lgkmcnt(7)
	v_mfma_f32_32x32x16_bf16 v[18:33], v[58:61], v[142:145], 0
	s_waitcnt lgkmcnt(6)
	v_mfma_f32_32x32x16_bf16 v[2:17], v[62:65], v[142:145], 0
	s_waitcnt lgkmcnt(5)
	v_mfma_f32_32x32x16_bf16 v[18:33], v[54:57], v[138:141], v[18:33]
	s_waitcnt lgkmcnt(4)
	v_mfma_f32_32x32x16_bf16 v[2:17], v[50:53], v[138:141], v[2:17]
	s_waitcnt lgkmcnt(3)
	v_mfma_f32_32x32x16_bf16 v[18:33], v[46:49], v[134:137], v[18:33]
	s_waitcnt lgkmcnt(2)
	v_mfma_f32_32x32x16_bf16 v[2:17], v[42:45], v[134:137], v[2:17]
	s_waitcnt lgkmcnt(1)
	v_mfma_f32_32x32x16_bf16 v[18:33], v[38:41], v[130:133], v[18:33]
	s_waitcnt lgkmcnt(0)
	v_mfma_f32_32x32x16_bf16 v[2:17], v[34:37], v[130:133], v[2:17]
	s_setprio 1
	v_lshlrev_b32_e32 v0, 2, v169
	v_or_b32_e32 v1, 32, v0
	v_cmp_le_u32_e32 vcc, v1, v128
	v_or_b32_e32 v1, 33, v0
	s_nop 6
	v_cndmask_b32_e32 v2, v242, v2, vcc
	v_cmp_lt_u32_e32 vcc, v0, v128
	s_nop 1
	v_cndmask_b32_e32 v19, v242, v19, vcc
	v_cmp_le_u32_e32 vcc, v0, v128
	s_nop 1
	v_cndmask_b32_e32 v18, v242, v18, vcc
	v_cmp_le_u32_e32 vcc, v1, v128
	v_or_b32_e32 v1, 2, v0
	s_nop 0
	v_cndmask_b32_e32 v3, v242, v3, vcc
	v_cmp_le_u32_e32 vcc, v1, v128
	v_or_b32_e32 v1, 34, v0
	s_nop 0
	v_cndmask_b32_e32 v20, v242, v20, vcc
	v_cmp_le_u32_e32 vcc, v1, v128
	v_or_b32_e32 v1, 3, v0
	s_nop 0
	v_cndmask_b32_e32 v4, v242, v4, vcc
	v_cmp_le_u32_e32 vcc, v1, v128
	v_or_b32_e32 v1, 35, v0
	s_nop 0
	v_cndmask_b32_e32 v21, v242, v21, vcc
	v_cmp_le_u32_e32 vcc, v1, v128
	v_or_b32_e32 v1, 8, v0
	s_nop 0
	v_cndmask_b32_e32 v5, v242, v5, vcc
	v_cmp_le_u32_e32 vcc, v1, v128
	v_or_b32_e32 v1, 40, v0
	s_nop 0
	v_cndmask_b32_e32 v22, v242, v22, vcc
	v_cmp_le_u32_e32 vcc, v1, v128
	v_or_b32_e32 v1, 9, v0
	s_nop 0
	v_cndmask_b32_e32 v6, v242, v6, vcc
	v_cmp_le_u32_e32 vcc, v1, v128
	v_or_b32_e32 v1, 41, v0
	s_nop 0
	v_cndmask_b32_e32 v23, v242, v23, vcc
	v_cmp_le_u32_e32 vcc, v1, v128
	v_or_b32_e32 v1, 10, v0
	s_nop 0
	v_cndmask_b32_e32 v7, v242, v7, vcc
	v_cmp_le_u32_e32 vcc, v1, v128
	v_or_b32_e32 v1, 42, v0
	s_nop 0
	v_cndmask_b32_e32 v24, v242, v24, vcc
	v_cmp_le_u32_e32 vcc, v1, v128
	v_or_b32_e32 v1, 11, v0
	s_nop 0
	v_cndmask_b32_e32 v8, v242, v8, vcc
	v_cmp_le_u32_e32 vcc, v1, v128
	v_or_b32_e32 v1, 43, v0
	s_nop 0
	v_cndmask_b32_e32 v25, v242, v25, vcc
	v_cmp_le_u32_e32 vcc, v1, v128
	v_or_b32_e32 v1, 16, v0
	s_nop 0
	v_cndmask_b32_e32 v9, v242, v9, vcc
	v_cmp_le_u32_e32 vcc, v1, v128
	v_or_b32_e32 v1, 48, v0
	s_nop 0
	v_cndmask_b32_e32 v26, v242, v26, vcc
	v_cmp_le_u32_e32 vcc, v1, v128
	v_or_b32_e32 v1, 17, v0
	s_nop 0
	v_cndmask_b32_e32 v10, v242, v10, vcc
	v_cmp_le_u32_e32 vcc, v1, v128
	v_or_b32_e32 v1, 49, v0
	s_nop 0
	v_cndmask_b32_e32 v27, v242, v27, vcc
	v_cmp_le_u32_e32 vcc, v1, v128
	v_or_b32_e32 v1, 18, v0
	s_nop 0
	v_cndmask_b32_e32 v11, v242, v11, vcc
	v_cmp_le_u32_e32 vcc, v1, v128
	v_or_b32_e32 v1, 50, v0
	s_nop 0
	v_cndmask_b32_e32 v28, v242, v28, vcc
	v_cmp_le_u32_e32 vcc, v1, v128
	v_or_b32_e32 v1, 19, v0
	s_nop 0
	v_cndmask_b32_e32 v12, v242, v12, vcc
	v_cmp_le_u32_e32 vcc, v1, v128
	v_or_b32_e32 v1, 51, v0
	s_nop 0
	v_cndmask_b32_e32 v29, v242, v29, vcc
	v_cmp_le_u32_e32 vcc, v1, v128
	v_or_b32_e32 v1, 24, v0
	s_nop 0
	v_cndmask_b32_e32 v13, v242, v13, vcc
	v_cmp_le_u32_e32 vcc, v1, v128
	v_or_b32_e32 v1, 56, v0
	s_nop 0
	v_cndmask_b32_e32 v30, v242, v30, vcc
	v_cmp_le_u32_e32 vcc, v1, v128
	v_or_b32_e32 v1, 25, v0
	s_nop 0
	v_cndmask_b32_e32 v14, v242, v14, vcc
	v_cmp_le_u32_e32 vcc, v1, v128
	v_or_b32_e32 v1, 57, v0
	s_nop 0
	v_cndmask_b32_e32 v31, v242, v31, vcc
	v_cmp_le_u32_e32 vcc, v1, v128
	v_or_b32_e32 v1, 26, v0
	s_nop 0
	v_cndmask_b32_e32 v15, v242, v15, vcc
	v_cmp_le_u32_e32 vcc, v1, v128
	v_or_b32_e32 v1, 58, v0
	s_nop 0
	v_cndmask_b32_e32 v32, v242, v32, vcc
	v_cmp_le_u32_e32 vcc, v1, v128
	v_or_b32_e32 v1, 27, v0
	v_or_b32_e32 v0, 59, v0
	v_cndmask_b32_e32 v16, v242, v16, vcc
	v_cmp_le_u32_e32 vcc, v1, v128
	s_nop 1
	v_cndmask_b32_e32 v33, v242, v33, vcc
	v_cmp_le_u32_e32 vcc, v0, v128
	s_nop 1
	v_cndmask_b32_e32 v17, v242, v17, vcc
	s_nop 15
	s_nop 7
	v_cmp_gt_u32_e32 vcc, 32, v166
	v_max3_f32 v0, v18, v19, v2
	v_max3_f32 v1, v20, v21, v3
	s_nop 0
	v_max3_f32 v0, v0, v4, v5
	v_max3_f32 v1, v1, v24, v25
	s_nop 0
	v_max3_f32 v0, v0, v22, v23
	v_max3_f32 v1, v1, v8, v9
	s_nop 0
	v_max3_f32 v0, v0, v6, v7
	v_max3_f32 v1, v1, v28, v29
	s_nop 0
	v_max3_f32 v0, v0, v26, v27
	v_max3_f32 v1, v1, v12, v13
	s_nop 0
	v_max3_f32 v0, v0, v10, v11
	v_max3_f32 v1, v1, v32, v33
	s_nop 0
	v_max3_f32 v0, v0, v30, v31
	v_max3_f32 v1, v1, v16, v17
	s_nop 0
	v_max3_f32 v0, v0, v14, v15
	s_nop 0
	v_max_f32_e32 v0, v0, v1
	s_nop 0
	v_mov_b32_e32 v1, v0
	s_nop 1
	v_permlane32_swap_b32_e32 v0, v1
	v_max_f32_e32 v34, v0, v1
	s_nop 0
	v_exp_f32_e64 v97, -v34
	s_and_saveexec_b64 s[40:41], vcc
	v_lshl_add_u32 v0, v170, 2, s53
	ds_write_b32 v0, v97
	s_or_b64 exec, exec, s[40:41]
	v_mov_b32_e32 v1, v2
	v_mov_b32_e32 v2, v19
	v_pk_add_f32 v[68:69], v[2:3], v[34:35] op_sel_hi:[1,0] neg_lo:[0,1] neg_hi:[0,1]
	v_mov_b32_e32 v2, v20
	v_mov_b32_e32 v3, v4
	v_pk_add_f32 v[72:73], v[2:3], v[34:35] op_sel_hi:[1,0] neg_lo:[0,1] neg_hi:[0,1]
	v_mov_b32_e32 v2, v22
	v_mov_b32_e32 v3, v6
	v_pk_add_f32 v[70:71], v[2:3], v[34:35] op_sel_hi:[1,0] neg_lo:[0,1] neg_hi:[0,1]
	v_mov_b32_e32 v2, v24
	v_mov_b32_e32 v3, v8
	v_pk_add_f32 v[78:79], v[2:3], v[34:35] op_sel_hi:[1,0] neg_lo:[0,1] neg_hi:[0,1]
	v_mov_b32_e32 v2, v26
	v_mov_b32_e32 v3, v10
	v_pk_add_f32 v[82:83], v[2:3], v[34:35] op_sel_hi:[1,0] neg_lo:[0,1] neg_hi:[0,1]
	v_mov_b32_e32 v2, v28
	v_mov_b32_e32 v3, v12
	v_add_f32_e32 v173, 0, v34
	v_mov_b32_e32 v0, v18
	v_pk_add_f32 v[86:87], v[2:3], v[34:35] op_sel_hi:[1,0] neg_lo:[0,1] neg_hi:[0,1]
	v_mov_b32_e32 v2, v30
	v_mov_b32_e32 v3, v14
	s_waitcnt lgkmcnt(0)
	v_pk_add_f32 v[66:67], v[0:1], v[34:35] op_sel_hi:[1,0] neg_lo:[0,1] neg_hi:[0,1]
	v_xor_b32_e32 v0, 0x80000000, v173
	v_mov_b32_e32 v4, v21
	v_mov_b32_e32 v6, v23
	v_mov_b32_e32 v8, v25
	v_mov_b32_e32 v10, v27
	v_mov_b32_e32 v12, v29
	v_pk_add_f32 v[90:91], v[2:3], v[34:35] op_sel_hi:[1,0] neg_lo:[0,1] neg_hi:[0,1]
	v_mov_b32_e32 v14, v31
	v_mov_b32_e32 v2, v32
	v_mov_b32_e32 v3, v16
	v_mov_b32_e32 v16, v33
	v_pk_add_f32 v[76:77], v[4:5], v[34:35] op_sel_hi:[1,0] neg_lo:[0,1] neg_hi:[0,1]
	v_pk_add_f32 v[74:75], v[6:7], v[34:35] op_sel_hi:[1,0] neg_lo:[0,1] neg_hi:[0,1]
	v_pk_add_f32 v[80:81], v[8:9], v[34:35] op_sel_hi:[1,0] neg_lo:[0,1] neg_hi:[0,1]
	v_pk_add_f32 v[84:85], v[10:11], v[34:35] op_sel_hi:[1,0] neg_lo:[0,1] neg_hi:[0,1]
	v_pk_add_f32 v[88:89], v[12:13], v[34:35] op_sel_hi:[1,0] neg_lo:[0,1] neg_hi:[0,1]
	v_pk_add_f32 v[92:93], v[14:15], v[34:35] op_sel_hi:[1,0] neg_lo:[0,1] neg_hi:[0,1]
	v_pk_add_f32 v[94:95], v[2:3], v[34:35] op_sel_hi:[1,0] neg_lo:[0,1] neg_hi:[0,1]
	v_pk_add_f32 v[32:33], v[16:17], v[34:35] op_sel_hi:[1,0] neg_lo:[0,1] neg_hi:[0,1]
	v_mov_b32_e32 v1, v0
	v_mov_b32_e32 v2, v0
	v_mov_b32_e32 v3, v0
	v_mov_b32_e32 v4, v0
	v_mov_b32_e32 v5, v0
	v_mov_b32_e32 v6, v0
	v_mov_b32_e32 v7, v0
	v_mov_b32_e32 v8, v0
	v_mov_b32_e32 v9, v0
	v_mov_b32_e32 v10, v0
	v_mov_b32_e32 v11, v0
	v_mov_b32_e32 v12, v0
	v_mov_b32_e32 v13, v0
	v_mov_b32_e32 v14, v0
	v_mov_b32_e32 v15, v0
.LBB0_176:
	s_waitcnt lgkmcnt(6)
	v_add_u32_e32 v64, s53, v162
	ds_read_b128 v[16:19], v64 offset:96
	ds_read_b128 v[20:23], v64 offset:64
	s_waitcnt lgkmcnt(2)
	ds_read_b128 v[34:37], v64 offset:32
	ds_read_b128 v[38:41], v64
	v_exp_f32_e32 v44, v70
	s_waitcnt lgkmcnt(3)
	v_pk_mul_f32 v[28:29], v[16:17], 0 op_sel_hi:[1,0]
	s_waitcnt lgkmcnt(2)
	v_pk_mul_f32 v[24:25], v[20:21], 0 op_sel_hi:[1,0]
	s_waitcnt lgkmcnt(1)
	v_pk_mul_f32 v[20:21], v[34:35], 0 op_sel_hi:[1,0]
	v_exp_f32_e32 v34, v66
	v_exp_f32_e32 v35, v67
	v_pk_mul_f32 v[26:27], v[22:23], 0 op_sel_hi:[1,0]
	v_pk_mul_f32 v[22:23], v[36:37], 0 op_sel_hi:[1,0]
	v_exp_f32_e32 v36, v68
	v_exp_f32_e32 v37, v69
	s_waitcnt lgkmcnt(0)
	v_pk_mul_f32 v[16:17], v[38:39], 0 op_sel_hi:[1,0]
	v_exp_f32_e32 v38, v72
	v_exp_f32_e32 v39, v73
	v_pk_mul_f32 v[30:31], v[18:19], 0 op_sel_hi:[1,0]
	v_pk_mul_f32 v[18:19], v[40:41], 0 op_sel_hi:[1,0]
	v_exp_f32_e32 v40, v76
	v_exp_f32_e32 v41, v77
	v_pk_add_f32 v[42:43], v[34:35], 0 op_sel_hi:[1,0]
	v_exp_f32_e32 v45, v71
	v_pk_add_f32 v[42:43], v[42:43], v[36:37]
	v_exp_f32_e32 v46, v74
	v_exp_f32_e32 v47, v75
	v_pk_add_f32 v[42:43], v[42:43], v[38:39]
	v_exp_f32_e32 v48, v78
	v_exp_f32_e32 v49, v79
	v_pk_add_f32 v[42:43], v[42:43], v[40:41]
	v_exp_f32_e32 v50, v80
	v_exp_f32_e32 v51, v81
	v_exp_f32_e32 v52, v82
	v_exp_f32_e32 v53, v83
	v_pk_add_f32 v[42:43], v[42:43], v[44:45]
	v_exp_f32_e32 v54, v84
	v_exp_f32_e32 v55, v85
	v_pk_add_f32 v[42:43], v[42:43], v[46:47]
	v_exp_f32_e32 v56, v86
	v_exp_f32_e32 v57, v87
	v_pk_add_f32 v[42:43], v[42:43], v[48:49]
	v_exp_f32_e32 v58, v88
	v_exp_f32_e32 v59, v89
	v_pk_add_f32 v[42:43], v[42:43], v[50:51]
	v_exp_f32_e32 v60, v90
	v_exp_f32_e32 v61, v91
	v_pk_add_f32 v[42:43], v[42:43], v[52:53]
	v_exp_f32_e32 v62, v92
	v_exp_f32_e32 v63, v93
	v_pk_add_f32 v[42:43], v[42:43], v[54:55]
	v_exp_f32_e32 v66, v94
	v_exp_f32_e32 v67, v95
	v_pk_add_f32 v[42:43], v[42:43], v[56:57]
	v_exp_f32_e32 v32, v32
	v_exp_f32_e32 v33, v33
	v_pk_add_f32 v[42:43], v[42:43], v[58:59]
	s_waitcnt vmcnt(0)
	s_waitcnt lgkmcnt(0)
	v_cvt_pk_bf16_f32 v146, v34, v36
	v_pk_add_f32 v[42:43], v[42:43], v[60:61]
	v_cvt_pk_bf16_f32 v147, v38, v40
	v_pk_add_f32 v[42:43], v[42:43], v[62:63]
	v_cvt_pk_bf16_f32 v148, v44, v46
	v_pk_add_f32 v[42:43], v[42:43], v[66:67]
	v_cvt_pk_bf16_f32 v149, v48, v50
	v_pk_add_f32 v[42:43], v[42:43], v[32:33]
	v_cvt_pk_bf16_f32 v150, v52, v54
	v_add_f32_e32 v172, v42, v43
	v_fmac_f32_e32 v172, 0, v97
	v_cvt_pk_bf16_f32 v151, v56, v58
	v_cvt_pk_bf16_f32 v152, v60, v62
	v_cvt_pk_bf16_f32 v153, v66, v32
	v_cvt_pk_bf16_f32 v154, v35, v37
	v_cvt_pk_bf16_f32 v155, v39, v41
	v_cvt_pk_bf16_f32 v156, v45, v47
	v_cvt_pk_bf16_f32 v157, v49, v51
	v_cvt_pk_bf16_f32 v158, v53, v55
	v_cvt_pk_bf16_f32 v159, v57, v59
	v_cvt_pk_bf16_f32 v160, v61, v63
	v_cvt_pk_bf16_f32 v161, v67, v33
	s_andn2_b64 vcc, exec, s[88:89]
	s_mov_b32 s15, 1
	s_barrier
	s_cbranch_vccnz .LBB0_197
	ds_read_b64_tr_b16 v[32:33], v163 offset:16384
	ds_read_b64_tr_b16 v[34:35], v163 offset:16896
	ds_read_b64_tr_b16 v[36:37], v163 offset:17408
	ds_read_b64_tr_b16 v[38:39], v163 offset:17920
	ds_read_b64_tr_b16 v[40:41], v163 offset:18432
	ds_read_b64_tr_b16 v[42:43], v163 offset:18944
	ds_read_b64_tr_b16 v[44:45], v163 offset:19456
	ds_read_b64_tr_b16 v[46:47], v163 offset:19968
	ds_read_b64_tr_b16 v[48:49], v163 offset:20480
	ds_read_b64_tr_b16 v[50:51], v163 offset:20992
	ds_read_b64_tr_b16 v[52:53], v163 offset:21504
	ds_read_b64_tr_b16 v[54:55], v163 offset:22016
	ds_read_b64_tr_b16 v[56:57], v163 offset:22528
	ds_read_b64_tr_b16 v[58:59], v163 offset:23040
	ds_read_b64_tr_b16 v[60:61], v163 offset:23552
	ds_read_b64_tr_b16 v[62:63], v163 offset:24064
	ds_read_b64_tr_b16 v[66:67], v163 offset:24576
	ds_read_b64_tr_b16 v[68:69], v163 offset:25088
	ds_read_b64_tr_b16 v[70:71], v163 offset:25600
	ds_read_b64_tr_b16 v[72:73], v163 offset:26112
	ds_read_b64_tr_b16 v[74:75], v163 offset:26624
	ds_read_b64_tr_b16 v[76:77], v163 offset:27136
	ds_read_b64_tr_b16 v[174:175], v163 offset:27648
	ds_read_b64_tr_b16 v[176:177], v163 offset:28160
	ds_read_b64_tr_b16 v[178:179], v163 offset:28672
	ds_read_b64_tr_b16 v[180:181], v163 offset:29184
	ds_read_b64_tr_b16 v[182:183], v163 offset:29696
	ds_read_b64_tr_b16 v[184:185], v163 offset:30208
	ds_read_b64_tr_b16 v[186:187], v163 offset:30720
	ds_read_b64_tr_b16 v[188:189], v163 offset:31232
	ds_read_b64_tr_b16 v[190:191], v163 offset:31744
	ds_read_b64_tr_b16 v[192:193], v163 offset:32256
	v_cmp_gt_u32_e64 s[40:41], 32, v166
	v_lshl_add_u32 v65, v170, 2, s53
	s_setprio 1
	s_waitcnt lgkmcnt(14)
	v_mfma_f32_32x32x16_bf16 v[112:127], v[146:149], v[32:35], v[16:31]
	v_mfma_f32_32x32x16_bf16 v[96:111], v[146:149], v[48:51], v[16:31]
	v_mfma_f32_32x32x16_bf16 v[80:95], v[146:149], v[66:69], v[16:31]
	s_waitcnt lgkmcnt(6)
	v_mfma_f32_32x32x16_bf16 v[16:31], v[146:149], v[178:181], v[16:31]
	v_mfma_f32_32x32x16_bf16 v[112:127], v[150:153], v[36:39], v[112:127]
	v_mfma_f32_32x32x16_bf16 v[96:111], v[150:153], v[52:55], v[96:111]
	v_mfma_f32_32x32x16_bf16 v[80:95], v[150:153], v[70:73], v[80:95]
	s_waitcnt lgkmcnt(4)
	v_mfma_f32_32x32x16_bf16 v[16:31], v[150:153], v[182:185], v[16:31]
	v_mfma_f32_32x32x16_bf16 v[112:127], v[154:157], v[40:43], v[112:127]
	v_mfma_f32_32x32x16_bf16 v[96:111], v[154:157], v[56:59], v[96:111]
	v_mfma_f32_32x32x16_bf16 v[80:95], v[154:157], v[74:77], v[80:95]
	s_waitcnt lgkmcnt(2)
	v_mfma_f32_32x32x16_bf16 v[16:31], v[154:157], v[186:189], v[16:31]
	v_mfma_f32_32x32x16_bf16 v[112:127], v[158:161], v[44:47], v[112:127]
	v_mfma_f32_32x32x16_bf16 v[96:111], v[158:161], v[60:63], v[96:111]
	v_mfma_f32_32x32x16_bf16 v[80:95], v[158:161], v[174:177], v[80:95]
	s_waitcnt lgkmcnt(0)
	v_mfma_f32_32x32x16_bf16 v[16:31], v[158:161], v[190:193], v[16:31]
	s_setprio 1
	ds_read_b128 v[48:51], v171 offset:32768
	ds_read_b128 v[66:69], v171 offset:33280
	ds_read_b128 v[70:73], v171 offset:34816
	ds_read_b128 v[74:77], v171 offset:35328
	ds_read_b128 v[146:149], v171 offset:36864
	ds_read_b128 v[150:153], v171 offset:37376
	ds_read_b128 v[154:157], v171 offset:38912
	ds_read_b128 v[158:161], v171 offset:39424
	s_setprio 1
	s_waitcnt lgkmcnt(7)
	v_mfma_f32_32x32x16_bf16 v[32:47], v[48:51], v[142:145], v[0:15]
	s_waitcnt lgkmcnt(6)
	v_mfma_f32_32x32x16_bf16 v[48:63], v[66:69], v[142:145], v[0:15]
	s_waitcnt lgkmcnt(5)
	v_mfma_f32_32x32x16_bf16 v[32:47], v[70:73], v[138:141], v[32:47]
	s_waitcnt lgkmcnt(4)
	v_mfma_f32_32x32x16_bf16 v[48:63], v[74:77], v[138:141], v[48:63]
	s_waitcnt lgkmcnt(3)
	v_mfma_f32_32x32x16_bf16 v[32:47], v[146:149], v[134:137], v[32:47]
	s_waitcnt lgkmcnt(2)
	v_mfma_f32_32x32x16_bf16 v[48:63], v[150:153], v[134:137], v[48:63]
	s_waitcnt lgkmcnt(1)
	v_mfma_f32_32x32x16_bf16 v[32:47], v[154:157], v[130:133], v[32:47]
	s_waitcnt lgkmcnt(0)
	v_mfma_f32_32x32x16_bf16 v[48:63], v[158:161], v[130:133], v[48:63]
	s_setprio 1
	s_nop 15
	s_nop 7
	s_nop 0
	v_max3_f32 v66, v32, v33, v48
	v_max3_f32 v67, v34, v35, v49
	s_nop 0
	v_max3_f32 v66, v66, v50, v51
	v_max3_f32 v67, v67, v38, v39
	s_nop 0
	v_max3_f32 v66, v66, v36, v37
	v_max3_f32 v67, v67, v54, v55
	s_nop 0
	v_max3_f32 v66, v66, v52, v53
	v_max3_f32 v67, v67, v42, v43
	s_nop 0
	v_max3_f32 v66, v66, v40, v41
	v_max3_f32 v67, v67, v58, v59
	s_nop 0
	v_max3_f32 v66, v66, v56, v57
	v_max3_f32 v67, v67, v46, v47
	s_nop 0
	v_max3_f32 v66, v66, v44, v45
	v_max3_f32 v67, v67, v62, v63
	s_nop 0
	v_max3_f32 v66, v66, v60, v61
	s_nop 0
	v_max_f32_e32 v66, v66, v67
	s_nop 0
	v_mov_b32_e32 v67, v66
	s_nop 1
	v_permlane32_swap_b32_e32 v66, v67
	v_max_f32_e32 v66, v66, v67
	s_nop 0
	v_cmp_lt_f32_e32 vcc, s4, v66
	s_cbranch_vccz .LBB0_181
	v_max_f32_e32 v0, v66, v66
	v_max_f32_e32 v2, 0, v0
	v_exp_f32_e64 v66, -v2
	s_and_saveexec_b64 s[76:77], s[40:41]
	ds_write_b32 v65, v66
	s_or_b64 exec, exec, s[76:77]
	s_waitcnt lgkmcnt(0)
	ds_read_b128 v[68:71], v64 offset:64
	ds_read_b128 v[72:75], v64 offset:96
	ds_read_b128 v[76:79], v64
	ds_read_b128 v[146:149], v64 offset:32
	v_add_f32_e32 v173, v173, v2
	v_xor_b32_e32 v0, 0x80000000, v173
	v_pk_add_f32 v[32:33], v[32:33], v[2:3] op_sel_hi:[1,0] neg_lo:[0,1] neg_hi:[0,1]
	v_pk_add_f32 v[48:49], v[48:49], v[2:3] op_sel_hi:[1,0] neg_lo:[0,1] neg_hi:[0,1]
	v_pk_add_f32 v[34:35], v[34:35], v[2:3] op_sel_hi:[1,0] neg_lo:[0,1] neg_hi:[0,1]
	v_pk_add_f32 v[50:51], v[50:51], v[2:3] op_sel_hi:[1,0] neg_lo:[0,1] neg_hi:[0,1]
	v_pk_add_f32 v[36:37], v[36:37], v[2:3] op_sel_hi:[1,0] neg_lo:[0,1] neg_hi:[0,1]
	v_pk_add_f32 v[52:53], v[52:53], v[2:3] op_sel_hi:[1,0] neg_lo:[0,1] neg_hi:[0,1]
	v_pk_add_f32 v[38:39], v[38:39], v[2:3] op_sel_hi:[1,0] neg_lo:[0,1] neg_hi:[0,1]
	v_pk_add_f32 v[54:55], v[54:55], v[2:3] op_sel_hi:[1,0] neg_lo:[0,1] neg_hi:[0,1]
	v_pk_add_f32 v[40:41], v[40:41], v[2:3] op_sel_hi:[1,0] neg_lo:[0,1] neg_hi:[0,1]
	v_pk_add_f32 v[56:57], v[56:57], v[2:3] op_sel_hi:[1,0] neg_lo:[0,1] neg_hi:[0,1]
	v_pk_add_f32 v[42:43], v[42:43], v[2:3] op_sel_hi:[1,0] neg_lo:[0,1] neg_hi:[0,1]
	v_pk_add_f32 v[58:59], v[58:59], v[2:3] op_sel_hi:[1,0] neg_lo:[0,1] neg_hi:[0,1]
	v_pk_add_f32 v[44:45], v[44:45], v[2:3] op_sel_hi:[1,0] neg_lo:[0,1] neg_hi:[0,1]
	v_pk_add_f32 v[60:61], v[60:61], v[2:3] op_sel_hi:[1,0] neg_lo:[0,1] neg_hi:[0,1]
	v_pk_add_f32 v[46:47], v[46:47], v[2:3] op_sel_hi:[1,0] neg_lo:[0,1] neg_hi:[0,1]
	v_pk_add_f32 v[62:63], v[62:63], v[2:3] op_sel_hi:[1,0] neg_lo:[0,1] neg_hi:[0,1]
	v_mov_b32_e32 v1, v0
	v_mov_b32_e32 v2, v0
	v_mov_b32_e32 v3, v0
	v_mov_b32_e32 v4, v0
	v_mov_b32_e32 v5, v0
	v_mov_b32_e32 v6, v0
	v_mov_b32_e32 v7, v0
	v_mov_b32_e32 v8, v0
	v_mov_b32_e32 v9, v0
	v_mov_b32_e32 v10, v0
	v_mov_b32_e32 v11, v0
	v_mov_b32_e32 v12, v0
	v_mov_b32_e32 v13, v0
	v_mov_b32_e32 v14, v0
	v_mov_b32_e32 v15, v0
	s_waitcnt lgkmcnt(2)
	v_pk_mul_f32 v[124:125], v[124:125], v[72:73]
	v_pk_mul_f32 v[120:121], v[120:121], v[68:69]
	s_waitcnt lgkmcnt(0)
	v_pk_mul_f32 v[116:117], v[116:117], v[146:147]
	v_pk_mul_f32 v[126:127], v[126:127], v[74:75]
	v_pk_mul_f32 v[122:123], v[122:123], v[70:71]
	v_pk_mul_f32 v[118:119], v[118:119], v[148:149]
	v_pk_mul_f32 v[114:115], v[114:115], v[78:79]
	v_pk_mul_f32 v[112:113], v[112:113], v[76:77]
	v_pk_mul_f32 v[108:109], v[108:109], v[72:73]
	v_pk_mul_f32 v[104:105], v[104:105], v[68:69]
	v_pk_mul_f32 v[100:101], v[100:101], v[146:147]
	v_pk_mul_f32 v[110:111], v[110:111], v[74:75]
	v_pk_mul_f32 v[106:107], v[106:107], v[70:71]
	v_pk_mul_f32 v[102:103], v[102:103], v[148:149]
	v_pk_mul_f32 v[98:99], v[98:99], v[78:79]
	v_pk_mul_f32 v[96:97], v[96:97], v[76:77]
	v_pk_mul_f32 v[92:93], v[92:93], v[72:73]
	v_pk_mul_f32 v[88:89], v[88:89], v[68:69]
	v_pk_mul_f32 v[84:85], v[84:85], v[146:147]
	v_pk_mul_f32 v[94:95], v[94:95], v[74:75]
	v_pk_mul_f32 v[90:91], v[90:91], v[70:71]
	v_pk_mul_f32 v[86:87], v[86:87], v[148:149]
	v_pk_mul_f32 v[82:83], v[82:83], v[78:79]
	v_pk_mul_f32 v[80:81], v[80:81], v[76:77]
	v_pk_mul_f32 v[28:29], v[28:29], v[72:73]
	v_pk_mul_f32 v[24:25], v[24:25], v[68:69]
	v_pk_mul_f32 v[20:21], v[20:21], v[146:147]
	v_pk_mul_f32 v[30:31], v[30:31], v[74:75]
	v_pk_mul_f32 v[26:27], v[26:27], v[70:71]
	v_pk_mul_f32 v[22:23], v[22:23], v[148:149]
	v_pk_mul_f32 v[18:19], v[18:19], v[78:79]
	v_pk_mul_f32 v[16:17], v[16:17], v[76:77]
	v_mul_f32_e32 v172, v172, v66

.LBB0_186:
	s_add_i32 s3, s65, 0xffff0000
	s_add_i32 s65, s65, 0x8000
	s_and_b32 s8, s65, 0x18000
	v_add_u32_e32 v78, s8, v163
	ds_read_b64_tr_b16 v[32:33], v78 offset:16384
	ds_read_b64_tr_b16 v[34:35], v78 offset:16896
	ds_read_b64_tr_b16 v[36:37], v78 offset:17408
	ds_read_b64_tr_b16 v[38:39], v78 offset:17920
	ds_read_b64_tr_b16 v[40:41], v78 offset:18432
	ds_read_b64_tr_b16 v[42:43], v78 offset:18944
	ds_read_b64_tr_b16 v[44:45], v78 offset:19456
	ds_read_b64_tr_b16 v[46:47], v78 offset:19968
	ds_read_b64_tr_b16 v[48:49], v78 offset:20480
	ds_read_b64_tr_b16 v[50:51], v78 offset:20992
	ds_read_b64_tr_b16 v[52:53], v78 offset:21504
	ds_read_b64_tr_b16 v[54:55], v78 offset:22016
	ds_read_b64_tr_b16 v[56:57], v78 offset:22528
	ds_read_b64_tr_b16 v[58:59], v78 offset:23040
	ds_read_b64_tr_b16 v[60:61], v78 offset:23552
	ds_read_b64_tr_b16 v[62:63], v78 offset:24064
	ds_read_b64_tr_b16 v[66:67], v78 offset:24576
	ds_read_b64_tr_b16 v[68:69], v78 offset:25088
	ds_read_b64_tr_b16 v[70:71], v78 offset:25600
	ds_read_b64_tr_b16 v[72:73], v78 offset:26112
	ds_read_b64_tr_b16 v[74:75], v78 offset:26624
	ds_read_b64_tr_b16 v[76:77], v78 offset:27136
	ds_read_b64_tr_b16 v[174:175], v78 offset:27648
	ds_read_b64_tr_b16 v[176:177], v78 offset:28160
	ds_read_b64_tr_b16 v[178:179], v78 offset:28672
	ds_read_b64_tr_b16 v[180:181], v78 offset:29184
	ds_read_b64_tr_b16 v[182:183], v78 offset:29696
	ds_read_b64_tr_b16 v[184:185], v78 offset:30208
	ds_read_b64_tr_b16 v[186:187], v78 offset:30720
	ds_read_b64_tr_b16 v[188:189], v78 offset:31232
	ds_read_b64_tr_b16 v[190:191], v78 offset:31744
	ds_read_b64_tr_b16 v[192:193], v78 offset:32256
	s_setprio 1
	s_waitcnt lgkmcnt(14)
	v_mfma_f32_32x32x16_bf16 v[112:127], v[146:149], v[32:35], v[112:127]
	v_mfma_f32_32x32x16_bf16 v[96:111], v[146:149], v[48:51], v[96:111]
	v_mfma_f32_32x32x16_bf16 v[80:95], v[146:149], v[66:69], v[80:95]
	s_waitcnt lgkmcnt(6)
	v_mfma_f32_32x32x16_bf16 v[16:31], v[146:149], v[178:181], v[16:31]
	v_mfma_f32_32x32x16_bf16 v[112:127], v[150:153], v[36:39], v[112:127]
	v_mfma_f32_32x32x16_bf16 v[96:111], v[150:153], v[52:55], v[96:111]
	v_mfma_f32_32x32x16_bf16 v[80:95], v[150:153], v[70:73], v[80:95]
	s_waitcnt lgkmcnt(4)
	v_mfma_f32_32x32x16_bf16 v[16:31], v[150:153], v[182:185], v[16:31]
	v_mfma_f32_32x32x16_bf16 v[112:127], v[154:157], v[40:43], v[112:127]
	v_mfma_f32_32x32x16_bf16 v[96:111], v[154:157], v[56:59], v[96:111]
	v_mfma_f32_32x32x16_bf16 v[80:95], v[154:157], v[74:77], v[80:95]
	s_waitcnt lgkmcnt(2)
	v_mfma_f32_32x32x16_bf16 v[16:31], v[154:157], v[186:189], v[16:31]
	v_mfma_f32_32x32x16_bf16 v[112:127], v[158:161], v[44:47], v[112:127]
	v_mfma_f32_32x32x16_bf16 v[96:111], v[158:161], v[60:63], v[96:111]
	v_mfma_f32_32x32x16_bf16 v[80:95], v[158:161], v[174:177], v[80:95]
	s_waitcnt lgkmcnt(0)
	v_mfma_f32_32x32x16_bf16 v[16:31], v[158:161], v[190:193], v[16:31]
	s_setprio 1
	s_and_b32 s3, s3, 0x18000
	v_add_u32_e32 v32, s3, v171
	ds_read_b128 v[48:51], v32
	ds_read_b128 v[66:69], v32 offset:512
	ds_read_b128 v[70:73], v32 offset:2048
	ds_read_b128 v[74:77], v32 offset:2560
	ds_read_b128 v[146:149], v32 offset:4096
	ds_read_b128 v[150:153], v32 offset:4608
	ds_read_b128 v[154:157], v32 offset:6144
	ds_read_b128 v[158:161], v32 offset:6656
	s_setprio 1
	s_waitcnt lgkmcnt(7)
	v_mfma_f32_32x32x16_bf16 v[32:47], v[48:51], v[142:145], v[0:15]
	s_waitcnt lgkmcnt(6)
	v_mfma_f32_32x32x16_bf16 v[48:63], v[66:69], v[142:145], v[0:15]
	s_waitcnt lgkmcnt(5)
	v_mfma_f32_32x32x16_bf16 v[32:47], v[70:73], v[138:141], v[32:47]
	s_waitcnt lgkmcnt(4)
	v_mfma_f32_32x32x16_bf16 v[48:63], v[74:77], v[138:141], v[48:63]
	s_waitcnt lgkmcnt(3)
	v_mfma_f32_32x32x16_bf16 v[32:47], v[146:149], v[134:137], v[32:47]
	s_waitcnt lgkmcnt(2)
	v_mfma_f32_32x32x16_bf16 v[48:63], v[150:153], v[134:137], v[48:63]
	s_waitcnt lgkmcnt(1)
	v_mfma_f32_32x32x16_bf16 v[32:47], v[154:157], v[130:133], v[32:47]
	s_waitcnt lgkmcnt(0)
	v_mfma_f32_32x32x16_bf16 v[48:63], v[158:161], v[130:133], v[48:63]
	s_setprio 1
	s_nop 15
	s_nop 7
	s_nop 0
	v_max3_f32 v66, v32, v33, v48
	v_max3_f32 v67, v34, v35, v49
	s_nop 0
	v_max3_f32 v66, v66, v50, v51
	v_max3_f32 v67, v67, v38, v39
	s_nop 0
	v_max3_f32 v66, v66, v36, v37
	v_max3_f32 v67, v67, v54, v55
	s_nop 0
	v_max3_f32 v66, v66, v52, v53
	v_max3_f32 v67, v67, v42, v43
	s_nop 0
	v_max3_f32 v66, v66, v40, v41
	v_max3_f32 v67, v67, v58, v59
	s_nop 0
	v_max3_f32 v66, v66, v56, v57
	v_max3_f32 v67, v67, v46, v47
	s_nop 0
	v_max3_f32 v66, v66, v44, v45
	v_max3_f32 v67, v67, v62, v63
	s_nop 0
	v_max3_f32 v66, v66, v60, v61
	s_nop 0
	v_max_f32_e32 v66, v66, v67
	s_nop 0
	v_mov_b32_e32 v67, v66
	s_nop 1
	v_permlane32_swap_b32_e32 v66, v67
	v_max_f32_e32 v66, v66, v67
	s_nop 0
	v_cmp_lt_f32_e32 vcc, s4, v66
	s_cbranch_vccz .LBB0_190
	v_max_f32_e32 v0, v66, v66
	v_max_f32_e32 v2, 0, v0
	v_exp_f32_e64 v66, -v2
	s_and_saveexec_b64 s[94:95], s[40:41]
	ds_write_b32 v65, v66
	s_or_b64 exec, exec, s[94:95]
	s_waitcnt lgkmcnt(0)
	ds_read_b128 v[68:71], v64 offset:64
	ds_read_b128 v[72:75], v64 offset:96
	ds_read_b128 v[76:79], v64
	ds_read_b128 v[146:149], v64 offset:32
	v_add_f32_e32 v173, v173, v2
	v_xor_b32_e32 v0, 0x80000000, v173
	v_pk_add_f32 v[32:33], v[32:33], v[2:3] op_sel_hi:[1,0] neg_lo:[0,1] neg_hi:[0,1]
	v_pk_add_f32 v[48:49], v[48:49], v[2:3] op_sel_hi:[1,0] neg_lo:[0,1] neg_hi:[0,1]
	v_pk_add_f32 v[34:35], v[34:35], v[2:3] op_sel_hi:[1,0] neg_lo:[0,1] neg_hi:[0,1]
	v_pk_add_f32 v[50:51], v[50:51], v[2:3] op_sel_hi:[1,0] neg_lo:[0,1] neg_hi:[0,1]
	v_pk_add_f32 v[36:37], v[36:37], v[2:3] op_sel_hi:[1,0] neg_lo:[0,1] neg_hi:[0,1]
	v_pk_add_f32 v[52:53], v[52:53], v[2:3] op_sel_hi:[1,0] neg_lo:[0,1] neg_hi:[0,1]
	v_pk_add_f32 v[38:39], v[38:39], v[2:3] op_sel_hi:[1,0] neg_lo:[0,1] neg_hi:[0,1]
	v_pk_add_f32 v[54:55], v[54:55], v[2:3] op_sel_hi:[1,0] neg_lo:[0,1] neg_hi:[0,1]
	v_pk_add_f32 v[40:41], v[40:41], v[2:3] op_sel_hi:[1,0] neg_lo:[0,1] neg_hi:[0,1]
	v_pk_add_f32 v[56:57], v[56:57], v[2:3] op_sel_hi:[1,0] neg_lo:[0,1] neg_hi:[0,1]
	v_pk_add_f32 v[42:43], v[42:43], v[2:3] op_sel_hi:[1,0] neg_lo:[0,1] neg_hi:[0,1]
	v_pk_add_f32 v[58:59], v[58:59], v[2:3] op_sel_hi:[1,0] neg_lo:[0,1] neg_hi:[0,1]
	v_pk_add_f32 v[44:45], v[44:45], v[2:3] op_sel_hi:[1,0] neg_lo:[0,1] neg_hi:[0,1]
	v_pk_add_f32 v[60:61], v[60:61], v[2:3] op_sel_hi:[1,0] neg_lo:[0,1] neg_hi:[0,1]
	v_pk_add_f32 v[46:47], v[46:47], v[2:3] op_sel_hi:[1,0] neg_lo:[0,1] neg_hi:[0,1]
	v_pk_add_f32 v[62:63], v[62:63], v[2:3] op_sel_hi:[1,0] neg_lo:[0,1] neg_hi:[0,1]
	v_mov_b32_e32 v1, v0
	v_mov_b32_e32 v2, v0
	v_mov_b32_e32 v3, v0
	v_mov_b32_e32 v4, v0
	v_mov_b32_e32 v5, v0
	v_mov_b32_e32 v6, v0
	v_mov_b32_e32 v7, v0
	v_mov_b32_e32 v8, v0
	v_mov_b32_e32 v9, v0
	v_mov_b32_e32 v10, v0
	v_mov_b32_e32 v11, v0
	v_mov_b32_e32 v12, v0
	v_mov_b32_e32 v13, v0
	v_mov_b32_e32 v14, v0
	v_mov_b32_e32 v15, v0
	s_waitcnt lgkmcnt(2)
	v_pk_mul_f32 v[124:125], v[124:125], v[72:73]
	v_pk_mul_f32 v[120:121], v[120:121], v[68:69]
	s_waitcnt lgkmcnt(0)
	v_pk_mul_f32 v[116:117], v[116:117], v[146:147]
	v_pk_mul_f32 v[126:127], v[126:127], v[74:75]
	v_pk_mul_f32 v[122:123], v[122:123], v[70:71]
	v_pk_mul_f32 v[118:119], v[118:119], v[148:149]
	v_pk_mul_f32 v[114:115], v[114:115], v[78:79]
	v_pk_mul_f32 v[112:113], v[112:113], v[76:77]
	v_pk_mul_f32 v[108:109], v[108:109], v[72:73]
	v_pk_mul_f32 v[104:105], v[104:105], v[68:69]
	v_pk_mul_f32 v[100:101], v[100:101], v[146:147]
	v_pk_mul_f32 v[110:111], v[110:111], v[74:75]
	v_pk_mul_f32 v[106:107], v[106:107], v[70:71]
	v_pk_mul_f32 v[102:103], v[102:103], v[148:149]
	v_pk_mul_f32 v[98:99], v[98:99], v[78:79]
	v_pk_mul_f32 v[96:97], v[96:97], v[76:77]
	v_pk_mul_f32 v[92:93], v[92:93], v[72:73]
	v_pk_mul_f32 v[88:89], v[88:89], v[68:69]
	v_pk_mul_f32 v[84:85], v[84:85], v[146:147]
	v_pk_mul_f32 v[94:95], v[94:95], v[74:75]
	v_pk_mul_f32 v[90:91], v[90:91], v[70:71]
	v_pk_mul_f32 v[86:87], v[86:87], v[148:149]
	v_pk_mul_f32 v[82:83], v[82:83], v[78:79]
	v_pk_mul_f32 v[80:81], v[80:81], v[76:77]
	v_pk_mul_f32 v[28:29], v[28:29], v[72:73]
	v_pk_mul_f32 v[24:25], v[24:25], v[68:69]
	v_pk_mul_f32 v[20:21], v[20:21], v[146:147]
	v_pk_mul_f32 v[30:31], v[30:31], v[74:75]
	v_pk_mul_f32 v[26:27], v[26:27], v[70:71]
	v_pk_mul_f32 v[22:23], v[22:23], v[148:149]
	v_pk_mul_f32 v[18:19], v[18:19], v[78:79]
	v_pk_mul_f32 v[16:17], v[16:17], v[76:77]
	v_mul_f32_e32 v172, v172, v66

.LBB0_196:
	s_lshl_b32 s3, s15, 15
	s_add_i32 s3, s3, 0x18000
	s_and_b32 s3, s3, 0x18000
	v_add_u32_e32 v32, s3, v163
	ds_read_b64_tr_b16 v[0:1], v32 offset:16384
	ds_read_b64_tr_b16 v[2:3], v32 offset:16896
	ds_read_b64_tr_b16 v[4:5], v32 offset:17408
	ds_read_b64_tr_b16 v[6:7], v32 offset:17920
	ds_read_b64_tr_b16 v[8:9], v32 offset:18432
	ds_read_b64_tr_b16 v[10:11], v32 offset:18944
	ds_read_b64_tr_b16 v[12:13], v32 offset:19456
	ds_read_b64_tr_b16 v[14:15], v32 offset:19968
	ds_read_b64_tr_b16 v[64:65], v32 offset:20480
	ds_read_b64_tr_b16 v[66:67], v32 offset:20992
	ds_read_b64_tr_b16 v[68:69], v32 offset:21504
	ds_read_b64_tr_b16 v[70:71], v32 offset:22016
	ds_read_b64_tr_b16 v[72:73], v32 offset:22528
	ds_read_b64_tr_b16 v[74:75], v32 offset:23040
	ds_read_b64_tr_b16 v[76:77], v32 offset:23552
	ds_read_b64_tr_b16 v[78:79], v32 offset:24064
	ds_read_b64_tr_b16 v[174:175], v32 offset:24576
	ds_read_b64_tr_b16 v[176:177], v32 offset:25088
	ds_read_b64_tr_b16 v[178:179], v32 offset:25600
	ds_read_b64_tr_b16 v[180:181], v32 offset:26112
	ds_read_b64_tr_b16 v[182:183], v32 offset:26624
	ds_read_b64_tr_b16 v[184:185], v32 offset:27136
	ds_read_b64_tr_b16 v[186:187], v32 offset:27648
	ds_read_b64_tr_b16 v[188:189], v32 offset:28160
	ds_read_b64_tr_b16 v[190:191], v32 offset:28672
	ds_read_b64_tr_b16 v[192:193], v32 offset:29184
	ds_read_b64_tr_b16 v[194:195], v32 offset:29696
	ds_read_b64_tr_b16 v[196:197], v32 offset:30208
	ds_read_b64_tr_b16 v[198:199], v32 offset:30720
	ds_read_b64_tr_b16 v[200:201], v32 offset:31232
	ds_read_b64_tr_b16 v[202:203], v32 offset:31744
	ds_read_b64_tr_b16 v[204:205], v32 offset:32256
	s_setprio 1
	s_waitcnt lgkmcnt(14)
	v_mfma_f32_32x32x16_bf16 v[32:47], v[146:149], v[0:3], v[112:127]
	v_mfma_f32_32x32x16_bf16 v[48:63], v[146:149], v[64:67], v[96:111]
	v_mfma_f32_32x32x16_bf16 v[32:47], v[150:153], v[4:7], v[32:47]
	v_mfma_f32_32x32x16_bf16 v[48:63], v[150:153], v[68:71], v[48:63]
	v_mfma_f32_32x32x16_bf16 v[32:47], v[154:157], v[8:11], v[32:47]
	v_mfma_f32_32x32x16_bf16 v[48:63], v[154:157], v[72:75], v[48:63]
	v_mfma_f32_32x32x16_bf16 v[32:47], v[158:161], v[12:15], v[32:47]
	v_mfma_f32_32x32x16_bf16 v[48:63], v[158:161], v[76:79], v[48:63]
	v_mfma_f32_32x32x16_bf16 v[64:79], v[146:149], v[174:177], v[80:95]
	s_waitcnt lgkmcnt(6)
	v_mfma_f32_32x32x16_bf16 v[0:15], v[146:149], v[190:193], v[16:31]
	v_mfma_f32_32x32x16_bf16 v[64:79], v[150:153], v[178:181], v[64:79]
	s_waitcnt lgkmcnt(4)
	v_mfma_f32_32x32x16_bf16 v[0:15], v[150:153], v[194:197], v[0:15]
	v_mfma_f32_32x32x16_bf16 v[64:79], v[154:157], v[182:185], v[64:79]
	s_waitcnt lgkmcnt(2)
	v_mfma_f32_32x32x16_bf16 v[0:15], v[154:157], v[198:201], v[0:15]
	v_mfma_f32_32x32x16_bf16 v[64:79], v[158:161], v[186:189], v[64:79]
	s_waitcnt lgkmcnt(0)
	v_mfma_f32_32x32x16_bf16 v[0:15], v[158:161], v[202:205], v[0:15]
	s_setprio 1
	s_cbranch_execnz .LBB0_224
	s_branch .LBB0_211

.LBB0_201:
	s_lshl_b32 s3, s15, 15
	s_add_i32 s8, s3, 0x18000
	s_and_b32 s8, s8, 0x18000
	v_add_u32_e32 v65, s8, v163
	ds_read_b64_tr_b16 v[32:33], v65 offset:16384
	ds_read_b64_tr_b16 v[34:35], v65 offset:16896
	ds_read_b64_tr_b16 v[36:37], v65 offset:17408
	ds_read_b64_tr_b16 v[38:39], v65 offset:17920
	ds_read_b64_tr_b16 v[40:41], v65 offset:18432
	ds_read_b64_tr_b16 v[42:43], v65 offset:18944
	ds_read_b64_tr_b16 v[44:45], v65 offset:19456
	ds_read_b64_tr_b16 v[46:47], v65 offset:19968
	ds_read_b64_tr_b16 v[48:49], v65 offset:20480
	ds_read_b64_tr_b16 v[50:51], v65 offset:20992
	ds_read_b64_tr_b16 v[52:53], v65 offset:21504
	ds_read_b64_tr_b16 v[54:55], v65 offset:22016
	ds_read_b64_tr_b16 v[56:57], v65 offset:22528
	ds_read_b64_tr_b16 v[58:59], v65 offset:23040
	ds_read_b64_tr_b16 v[60:61], v65 offset:23552
	ds_read_b64_tr_b16 v[62:63], v65 offset:24064
	ds_read_b64_tr_b16 v[66:67], v65 offset:24576
	ds_read_b64_tr_b16 v[68:69], v65 offset:25088
	ds_read_b64_tr_b16 v[70:71], v65 offset:25600
	ds_read_b64_tr_b16 v[72:73], v65 offset:26112
	ds_read_b64_tr_b16 v[74:75], v65 offset:26624
	ds_read_b64_tr_b16 v[76:77], v65 offset:27136
	ds_read_b64_tr_b16 v[174:175], v65 offset:27648
	ds_read_b64_tr_b16 v[176:177], v65 offset:28160
	ds_read_b64_tr_b16 v[178:179], v65 offset:28672
	ds_read_b64_tr_b16 v[180:181], v65 offset:29184
	ds_read_b64_tr_b16 v[182:183], v65 offset:29696
	ds_read_b64_tr_b16 v[184:185], v65 offset:30208
	ds_read_b64_tr_b16 v[186:187], v65 offset:30720
	ds_read_b64_tr_b16 v[188:189], v65 offset:31232
	ds_read_b64_tr_b16 v[190:191], v65 offset:31744
	ds_read_b64_tr_b16 v[192:193], v65 offset:32256
	s_setprio 1
	s_waitcnt lgkmcnt(14)
	v_mfma_f32_32x32x16_bf16 v[112:127], v[146:149], v[32:35], v[112:127]
	v_mfma_f32_32x32x16_bf16 v[96:111], v[146:149], v[48:51], v[96:111]
	v_mfma_f32_32x32x16_bf16 v[80:95], v[146:149], v[66:69], v[80:95]
	s_waitcnt lgkmcnt(6)
	v_mfma_f32_32x32x16_bf16 v[16:31], v[146:149], v[178:181], v[16:31]
	v_mfma_f32_32x32x16_bf16 v[112:127], v[150:153], v[36:39], v[112:127]
	v_mfma_f32_32x32x16_bf16 v[96:111], v[150:153], v[52:55], v[96:111]
	v_mfma_f32_32x32x16_bf16 v[80:95], v[150:153], v[70:73], v[80:95]
	s_waitcnt lgkmcnt(4)
	v_mfma_f32_32x32x16_bf16 v[16:31], v[150:153], v[182:185], v[16:31]
	v_mfma_f32_32x32x16_bf16 v[112:127], v[154:157], v[40:43], v[112:127]
	v_mfma_f32_32x32x16_bf16 v[96:111], v[154:157], v[56:59], v[96:111]
	v_mfma_f32_32x32x16_bf16 v[80:95], v[154:157], v[74:77], v[80:95]
	s_waitcnt lgkmcnt(2)
	v_mfma_f32_32x32x16_bf16 v[16:31], v[154:157], v[186:189], v[16:31]
	v_mfma_f32_32x32x16_bf16 v[112:127], v[158:161], v[44:47], v[112:127]
	v_mfma_f32_32x32x16_bf16 v[96:111], v[158:161], v[60:63], v[96:111]
	v_mfma_f32_32x32x16_bf16 v[80:95], v[158:161], v[174:177], v[80:95]
	s_waitcnt lgkmcnt(0)
	v_mfma_f32_32x32x16_bf16 v[16:31], v[158:161], v[190:193], v[16:31]
	s_setprio 1
	s_and_b32 s3, s3, 0x18000
	v_add_u32_e32 v32, s3, v171
	ds_read_b128 v[48:51], v32
	ds_read_b128 v[52:55], v32 offset:512
	ds_read_b128 v[56:59], v32 offset:2048
	ds_read_b128 v[60:63], v32 offset:2560
	ds_read_b128 v[66:69], v32 offset:4096
	ds_read_b128 v[70:73], v32 offset:4608
	ds_read_b128 v[74:77], v32 offset:6144
	ds_read_b128 v[146:149], v32 offset:6656
	s_lshl_b32 s3, s15, 6
	v_subrev_u32_e32 v65, s3, v128
	s_setprio 1
	s_waitcnt lgkmcnt(7)
	v_mfma_f32_32x32x16_bf16 v[32:47], v[48:51], v[142:145], v[0:15]
	s_waitcnt lgkmcnt(6)
	v_mfma_f32_32x32x16_bf16 v[0:15], v[52:55], v[142:145], v[0:15]
	s_waitcnt lgkmcnt(5)
	v_mfma_f32_32x32x16_bf16 v[32:47], v[56:59], v[138:141], v[32:47]
	s_waitcnt lgkmcnt(4)
	v_mfma_f32_32x32x16_bf16 v[0:15], v[60:63], v[138:141], v[0:15]
	s_waitcnt lgkmcnt(3)
	v_mfma_f32_32x32x16_bf16 v[32:47], v[66:69], v[134:137], v[32:47]
	s_waitcnt lgkmcnt(2)
	v_mfma_f32_32x32x16_bf16 v[0:15], v[70:73], v[134:137], v[0:15]
	s_waitcnt lgkmcnt(1)
	v_mfma_f32_32x32x16_bf16 v[32:47], v[74:77], v[130:133], v[32:47]
	s_waitcnt lgkmcnt(0)
	v_mfma_f32_32x32x16_bf16 v[0:15], v[146:149], v[130:133], v[0:15]
	s_setprio 1
	v_lshlrev_b32_e32 v48, 2, v169
	v_or_b32_e32 v49, 32, v48
	v_cmp_le_i32_e32 vcc, v49, v65
	v_or_b32_e32 v49, 33, v48
	s_nop 6
	v_cndmask_b32_e32 v0, v242, v0, vcc
	v_cmp_lt_i32_e32 vcc, v48, v65
	s_nop 1
	v_cndmask_b32_e32 v33, v242, v33, vcc
	v_cmp_le_i32_e32 vcc, v48, v65
	s_nop 1
	v_cndmask_b32_e32 v32, v242, v32, vcc
	v_cmp_le_i32_e32 vcc, v49, v65
	v_or_b32_e32 v49, 2, v48
	s_nop 0
	v_cndmask_b32_e32 v1, v242, v1, vcc
	v_cmp_le_i32_e32 vcc, v49, v65
	v_or_b32_e32 v49, 34, v48
	s_nop 0
	v_cndmask_b32_e32 v34, v242, v34, vcc
	v_cmp_le_i32_e32 vcc, v49, v65
	v_or_b32_e32 v49, 3, v48
	s_nop 0
	v_cndmask_b32_e32 v2, v242, v2, vcc
	v_cmp_le_i32_e32 vcc, v49, v65
	v_or_b32_e32 v49, 35, v48
	s_nop 0
	v_cndmask_b32_e32 v35, v242, v35, vcc
	v_cmp_le_i32_e32 vcc, v49, v65
	v_or_b32_e32 v49, 8, v48
	s_nop 0
	v_cndmask_b32_e32 v3, v242, v3, vcc
	v_cmp_le_i32_e32 vcc, v49, v65
	v_or_b32_e32 v49, 40, v48
	s_nop 0
	v_cndmask_b32_e32 v36, v242, v36, vcc
	v_cmp_le_i32_e32 vcc, v49, v65
	v_or_b32_e32 v49, 9, v48
	s_nop 0
	v_cndmask_b32_e32 v4, v242, v4, vcc
	v_cmp_le_i32_e32 vcc, v49, v65
	v_or_b32_e32 v49, 41, v48
	s_nop 0
	v_cndmask_b32_e32 v37, v242, v37, vcc
	v_cmp_le_i32_e32 vcc, v49, v65
	v_or_b32_e32 v49, 10, v48
	s_nop 0
	v_cndmask_b32_e32 v5, v242, v5, vcc
	v_cmp_le_i32_e32 vcc, v49, v65
	v_or_b32_e32 v49, 42, v48
	s_nop 0
	v_cndmask_b32_e32 v38, v242, v38, vcc
	v_cmp_le_i32_e32 vcc, v49, v65
	v_or_b32_e32 v49, 11, v48
	s_nop 0
	v_cndmask_b32_e32 v6, v242, v6, vcc
	v_cmp_le_i32_e32 vcc, v49, v65
	v_or_b32_e32 v49, 43, v48
	s_nop 0
	v_cndmask_b32_e32 v39, v242, v39, vcc
	v_cmp_le_i32_e32 vcc, v49, v65
	v_or_b32_e32 v49, 16, v48
	s_nop 0
	v_cndmask_b32_e32 v7, v242, v7, vcc
	v_cmp_le_i32_e32 vcc, v49, v65
	v_or_b32_e32 v49, 48, v48
	s_nop 0
	v_cndmask_b32_e32 v40, v242, v40, vcc
	v_cmp_le_i32_e32 vcc, v49, v65
	v_or_b32_e32 v49, 17, v48
	s_nop 0
	v_cndmask_b32_e32 v8, v242, v8, vcc
	v_cmp_le_i32_e32 vcc, v49, v65
	v_or_b32_e32 v49, 49, v48
	s_nop 0
	v_cndmask_b32_e32 v41, v242, v41, vcc
	v_cmp_le_i32_e32 vcc, v49, v65
	v_or_b32_e32 v49, 18, v48
	s_nop 0
	v_cndmask_b32_e32 v9, v242, v9, vcc
	v_cmp_le_i32_e32 vcc, v49, v65
	v_or_b32_e32 v49, 50, v48
	s_nop 0
	v_cndmask_b32_e32 v42, v242, v42, vcc
	v_cmp_le_i32_e32 vcc, v49, v65
	v_or_b32_e32 v49, 19, v48
	s_nop 0
	v_cndmask_b32_e32 v10, v242, v10, vcc
	v_cmp_le_i32_e32 vcc, v49, v65
	v_or_b32_e32 v49, 51, v48
	s_nop 0
	v_cndmask_b32_e32 v43, v242, v43, vcc
	v_cmp_le_i32_e32 vcc, v49, v65
	v_or_b32_e32 v49, 24, v48
	s_nop 0
	v_cndmask_b32_e32 v11, v242, v11, vcc
	v_cmp_le_i32_e32 vcc, v49, v65
	v_or_b32_e32 v49, 56, v48
	s_nop 0
	v_cndmask_b32_e32 v44, v242, v44, vcc
	v_cmp_le_i32_e32 vcc, v49, v65
	v_or_b32_e32 v49, 25, v48
	s_nop 0
	v_cndmask_b32_e32 v12, v242, v12, vcc
	v_cmp_le_i32_e32 vcc, v49, v65
	v_or_b32_e32 v49, 57, v48
	s_nop 0
	v_cndmask_b32_e32 v45, v242, v45, vcc
	v_cmp_le_i32_e32 vcc, v49, v65
	v_or_b32_e32 v49, 26, v48
	s_nop 0
	v_cndmask_b32_e32 v13, v242, v13, vcc
	v_cmp_le_i32_e32 vcc, v49, v65
	v_or_b32_e32 v49, 58, v48
	s_nop 0
	v_cndmask_b32_e32 v46, v242, v46, vcc
	v_cmp_le_i32_e32 vcc, v49, v65
	v_or_b32_e32 v49, 27, v48
	v_or_b32_e32 v48, 59, v48
	v_cndmask_b32_e32 v14, v242, v14, vcc
	v_cmp_le_i32_e32 vcc, v49, v65
	s_nop 1
	v_cndmask_b32_e32 v47, v242, v47, vcc
	v_cmp_le_i32_e32 vcc, v48, v65
	s_nop 1
	v_cndmask_b32_e32 v15, v242, v15, vcc
	s_nop 15
	s_nop 7
	s_nop 0
	v_max3_f32 v48, v32, v33, v0
	v_max3_f32 v49, v34, v35, v1
	s_nop 0
	v_max3_f32 v48, v48, v2, v3
	v_max3_f32 v49, v49, v38, v39
	s_nop 0
	v_max3_f32 v48, v48, v36, v37
	v_max3_f32 v49, v49, v6, v7
	s_nop 0
	v_max3_f32 v48, v48, v4, v5
	v_max3_f32 v49, v49, v42, v43
	s_nop 0
	v_max3_f32 v48, v48, v40, v41
	v_max3_f32 v49, v49, v10, v11
	s_nop 0
	v_max3_f32 v48, v48, v8, v9
	v_max3_f32 v49, v49, v46, v47
	s_nop 0
	v_max3_f32 v48, v48, v44, v45
	v_max3_f32 v49, v49, v14, v15
	s_nop 0
	v_max3_f32 v48, v48, v12, v13
	s_nop 0
	v_max_f32_e32 v48, v48, v49
	s_nop 0
	v_mov_b32_e32 v49, v48
	s_nop 1
	v_permlane32_swap_b32_e32 v48, v49
	v_max_f32_e32 v48, v48, v49
	s_nop 0
	v_cmp_lt_f32_e32 vcc, s4, v48
	s_cbranch_vccz .LBB0_205
	v_max_f32_e32 v48, v48, v48
	v_max_f32_e32 v48, 0, v48
	v_exp_f32_e64 v49, -v48
	v_cmp_gt_u32_e32 vcc, 32, v166
	s_and_saveexec_b64 s[76:77], vcc
	v_lshl_add_u32 v50, v170, 2, s53
	ds_write_b32 v50, v49
	s_or_b64 exec, exec, s[76:77]
	s_waitcnt lgkmcnt(0)
	ds_read_b128 v[50:53], v64
	ds_read_b128 v[54:57], v64 offset:32
	ds_read_b128 v[58:61], v64 offset:64
	ds_read_b128 v[62:65], v64 offset:96
	v_pk_add_f32 v[32:33], v[32:33], v[48:49] op_sel_hi:[1,0] neg_lo:[0,1] neg_hi:[0,1]
	v_pk_add_f32 v[0:1], v[0:1], v[48:49] op_sel_hi:[1,0] neg_lo:[0,1] neg_hi:[0,1]
	v_pk_add_f32 v[34:35], v[34:35], v[48:49] op_sel_hi:[1,0] neg_lo:[0,1] neg_hi:[0,1]
	v_pk_add_f32 v[2:3], v[2:3], v[48:49] op_sel_hi:[1,0] neg_lo:[0,1] neg_hi:[0,1]
	v_pk_add_f32 v[36:37], v[36:37], v[48:49] op_sel_hi:[1,0] neg_lo:[0,1] neg_hi:[0,1]
	v_pk_add_f32 v[4:5], v[4:5], v[48:49] op_sel_hi:[1,0] neg_lo:[0,1] neg_hi:[0,1]
	v_pk_add_f32 v[38:39], v[38:39], v[48:49] op_sel_hi:[1,0] neg_lo:[0,1] neg_hi:[0,1]
	v_pk_add_f32 v[6:7], v[6:7], v[48:49] op_sel_hi:[1,0] neg_lo:[0,1] neg_hi:[0,1]
	v_pk_add_f32 v[40:41], v[40:41], v[48:49] op_sel_hi:[1,0] neg_lo:[0,1] neg_hi:[0,1]
	v_pk_add_f32 v[8:9], v[8:9], v[48:49] op_sel_hi:[1,0] neg_lo:[0,1] neg_hi:[0,1]
	v_pk_add_f32 v[42:43], v[42:43], v[48:49] op_sel_hi:[1,0] neg_lo:[0,1] neg_hi:[0,1]
	v_pk_add_f32 v[10:11], v[10:11], v[48:49] op_sel_hi:[1,0] neg_lo:[0,1] neg_hi:[0,1]
	v_pk_add_f32 v[44:45], v[44:45], v[48:49] op_sel_hi:[1,0] neg_lo:[0,1] neg_hi:[0,1]
	v_pk_add_f32 v[12:13], v[12:13], v[48:49] op_sel_hi:[1,0] neg_lo:[0,1] neg_hi:[0,1]
	v_pk_add_f32 v[46:47], v[46:47], v[48:49] op_sel_hi:[1,0] neg_lo:[0,1] neg_hi:[0,1]
	v_pk_add_f32 v[14:15], v[14:15], v[48:49] op_sel_hi:[1,0] neg_lo:[0,1] neg_hi:[0,1]
	s_waitcnt lgkmcnt(0)
	v_pk_mul_f32 v[124:125], v[124:125], v[62:63]
	v_pk_mul_f32 v[120:121], v[120:121], v[58:59]
	v_pk_mul_f32 v[116:117], v[116:117], v[54:55]
	v_pk_mul_f32 v[126:127], v[126:127], v[64:65]
	v_pk_mul_f32 v[122:123], v[122:123], v[60:61]
	v_pk_mul_f32 v[118:119], v[118:119], v[56:57]
	v_pk_mul_f32 v[114:115], v[114:115], v[52:53]
	v_pk_mul_f32 v[112:113], v[112:113], v[50:51]
	v_pk_mul_f32 v[108:109], v[108:109], v[62:63]
	v_pk_mul_f32 v[104:105], v[104:105], v[58:59]
	v_pk_mul_f32 v[100:101], v[100:101], v[54:55]
	v_pk_mul_f32 v[110:111], v[110:111], v[64:65]
	v_pk_mul_f32 v[106:107], v[106:107], v[60:61]
	v_pk_mul_f32 v[102:103], v[102:103], v[56:57]
	v_pk_mul_f32 v[98:99], v[98:99], v[52:53]
	v_pk_mul_f32 v[96:97], v[96:97], v[50:51]
	v_pk_mul_f32 v[92:93], v[92:93], v[62:63]
	v_pk_mul_f32 v[88:89], v[88:89], v[58:59]
	v_pk_mul_f32 v[84:85], v[84:85], v[54:55]
	v_pk_mul_f32 v[94:95], v[94:95], v[64:65]
	v_pk_mul_f32 v[90:91], v[90:91], v[60:61]
	v_pk_mul_f32 v[86:87], v[86:87], v[56:57]
	v_pk_mul_f32 v[82:83], v[82:83], v[52:53]
	v_pk_mul_f32 v[80:81], v[80:81], v[50:51]
	v_pk_mul_f32 v[28:29], v[28:29], v[62:63]
	v_pk_mul_f32 v[24:25], v[24:25], v[58:59]
	v_pk_mul_f32 v[20:21], v[20:21], v[54:55]
	v_pk_mul_f32 v[30:31], v[30:31], v[64:65]
	v_pk_mul_f32 v[26:27], v[26:27], v[60:61]
	v_pk_mul_f32 v[22:23], v[22:23], v[56:57]
	v_pk_mul_f32 v[18:19], v[18:19], v[52:53]
	v_pk_mul_f32 v[16:17], v[16:17], v[50:51]
	v_mul_f32_e32 v172, v172, v49

.LBB0_213:
	s_lshl_b32 s3, s15, 15
	s_add_i32 s3, s3, 0x18000
	s_and_b32 s8, s3, 0x18000
	v_add_u32_e32 v32, s8, v163
	ds_read_b64_tr_b16 v[0:1], v32 offset:16384
	ds_read_b64_tr_b16 v[2:3], v32 offset:16896
	ds_read_b64_tr_b16 v[4:5], v32 offset:17408
	ds_read_b64_tr_b16 v[6:7], v32 offset:17920
	ds_read_b64_tr_b16 v[8:9], v32 offset:18432
	ds_read_b64_tr_b16 v[10:11], v32 offset:18944
	ds_read_b64_tr_b16 v[12:13], v32 offset:19456
	ds_read_b64_tr_b16 v[14:15], v32 offset:19968
	ds_read_b64_tr_b16 v[48:49], v32 offset:20480
	ds_read_b64_tr_b16 v[50:51], v32 offset:20992
	ds_read_b64_tr_b16 v[52:53], v32 offset:21504
	ds_read_b64_tr_b16 v[54:55], v32 offset:22016
	ds_read_b64_tr_b16 v[56:57], v32 offset:22528
	ds_read_b64_tr_b16 v[58:59], v32 offset:23040
	ds_read_b64_tr_b16 v[64:65], v32 offset:23552
	ds_read_b64_tr_b16 v[66:67], v32 offset:24064
	ds_read_b64_tr_b16 v[68:69], v32 offset:24576
	ds_read_b64_tr_b16 v[70:71], v32 offset:25088
	ds_read_b64_tr_b16 v[72:73], v32 offset:25600
	ds_read_b64_tr_b16 v[74:75], v32 offset:26112
	ds_read_b64_tr_b16 v[76:77], v32 offset:26624
	ds_read_b64_tr_b16 v[78:79], v32 offset:27136
	ds_read_b64_tr_b16 v[174:175], v32 offset:27648
	ds_read_b64_tr_b16 v[176:177], v32 offset:28160
	ds_read_b64_tr_b16 v[178:179], v32 offset:28672
	ds_read_b64_tr_b16 v[180:181], v32 offset:29184
	ds_read_b64_tr_b16 v[182:183], v32 offset:29696
	ds_read_b64_tr_b16 v[184:185], v32 offset:30208
	ds_read_b64_tr_b16 v[186:187], v32 offset:30720
	ds_read_b64_tr_b16 v[188:189], v32 offset:31232
	ds_read_b64_tr_b16 v[190:191], v32 offset:31744
	ds_read_b64_tr_b16 v[192:193], v32 offset:32256
	s_setprio 1
	s_waitcnt lgkmcnt(14)
	v_mfma_f32_32x32x16_bf16 v[112:127], v[146:149], v[0:3], v[112:127]
	v_mfma_f32_32x32x16_bf16 v[96:111], v[146:149], v[48:51], v[96:111]
	v_mfma_f32_32x32x16_bf16 v[80:95], v[146:149], v[68:71], v[80:95]
	s_waitcnt lgkmcnt(6)
	v_mfma_f32_32x32x16_bf16 v[16:31], v[146:149], v[178:181], v[16:31]
	v_mfma_f32_32x32x16_bf16 v[112:127], v[150:153], v[4:7], v[112:127]
	v_mfma_f32_32x32x16_bf16 v[96:111], v[150:153], v[52:55], v[96:111]
	v_mfma_f32_32x32x16_bf16 v[80:95], v[150:153], v[72:75], v[80:95]
	s_waitcnt lgkmcnt(4)
	v_mfma_f32_32x32x16_bf16 v[16:31], v[150:153], v[182:185], v[16:31]
	v_mfma_f32_32x32x16_bf16 v[112:127], v[154:157], v[8:11], v[112:127]
	v_mfma_f32_32x32x16_bf16 v[96:111], v[154:157], v[56:59], v[96:111]
	s_nop 10
	v_mov_b64_e32 v[32:33], v[112:113]
	v_mov_b64_e32 v[34:35], v[114:115]
	v_mov_b64_e32 v[36:37], v[116:117]
	v_mov_b64_e32 v[38:39], v[118:119]
	v_mov_b64_e32 v[40:41], v[120:121]
	v_mov_b64_e32 v[42:43], v[122:123]
	v_mov_b64_e32 v[44:45], v[124:125]
	v_mfma_f32_32x32x16_bf16 v[80:95], v[154:157], v[76:79], v[80:95]
	v_mov_b64_e32 v[48:49], v[96:97]
	v_mov_b64_e32 v[46:47], v[126:127]
	v_mov_b64_e32 v[50:51], v[98:99]
	v_mov_b64_e32 v[52:53], v[100:101]
	v_mov_b64_e32 v[54:55], v[102:103]
	v_mov_b64_e32 v[56:57], v[104:105]
	v_mov_b64_e32 v[58:59], v[106:107]
	s_waitcnt lgkmcnt(2)
	v_mfma_f32_32x32x16_bf16 v[16:31], v[154:157], v[186:189], v[16:31]
	v_mov_b64_e32 v[60:61], v[108:109]
	v_mov_b64_e32 v[62:63], v[110:111]
	v_mfma_f32_32x32x16_bf16 v[32:47], v[158:161], v[12:15], v[32:47]
	s_nop 8
	v_mov_b64_e32 v[0:1], v[16:17]
	v_mov_b64_e32 v[2:3], v[18:19]
	v_mov_b64_e32 v[4:5], v[20:21]
	v_mov_b64_e32 v[6:7], v[22:23]
	v_mov_b64_e32 v[8:9], v[24:25]
	v_mov_b64_e32 v[10:11], v[26:27]
	v_mov_b64_e32 v[12:13], v[28:29]
	v_mfma_f32_32x32x16_bf16 v[48:63], v[158:161], v[64:67], v[48:63]
	v_mov_b64_e32 v[64:65], v[80:81]
	v_mov_b64_e32 v[66:67], v[82:83]
	v_mov_b64_e32 v[68:69], v[84:85]
	v_mov_b64_e32 v[70:71], v[86:87]
	v_mov_b64_e32 v[72:73], v[88:89]
	v_mov_b64_e32 v[74:75], v[90:91]
	v_mov_b64_e32 v[76:77], v[92:93]
	v_mov_b64_e32 v[78:79], v[94:95]
	v_mov_b64_e32 v[14:15], v[30:31]
	s_nop 0
	v_mfma_f32_32x32x16_bf16 v[64:79], v[158:161], v[174:177], v[64:79]
	s_waitcnt lgkmcnt(0)
	v_mfma_f32_32x32x16_bf16 v[0:15], v[158:161], v[190:193], v[0:15]
	s_setprio 1
	s_mov_b64 s[76:77], -1
	s_and_b64 vcc, exec, s[40:41]
	s_cbranch_vccz .LBB0_215
	s_waitcnt vmcnt(0)
	s_mov_b64 s[76:77], 0

.LBB0_267:
	s_setprio 0
	v_mov_b32_e32 v16, v172
	s_nop 1
	v_permlane32_swap_b32_e32 v172, v16
	v_and_b32_e32 v17, 31, v166
	v_cmp_gt_u32_e32 vcc, 32, v166
	s_and_saveexec_b64 s[26:27], vcc
	s_cbranch_execz .LBB0_269
	v_add_f32_e32 v16, v172, v16
	v_cndmask_b32_e64 v18, v164, 1.0, s[80:81]
	v_div_scale_f32 v19, s[8:9], v16, v16, v18
	v_rcp_f32_e32 v20, v19
	s_nop 0
	v_fma_f32 v21, -v19, v20, 1.0
	v_fmac_f32_e32 v20, v21, v20
	v_div_scale_f32 v21, vcc, v18, v16, v18
	v_mul_f32_e32 v22, v21, v20
	v_fma_f32 v23, -v19, v22, v21
	v_fmac_f32_e32 v22, v23, v20
	v_fma_f32 v19, -v19, v22, v21
	v_div_fmas_f32 v19, v19, v20, v22
	v_div_fixup_f32 v16, v19, v16, v18
	v_lshl_add_u32 v18, v17, 2, s53
	ds_write_b32 v18, v16
